# mLSTM output walk: the two halves run two barriers apart (one in the state-only pass)
# baseline (speedup 1.0000x reference)
.LBB0_511:
	v_or_b32_e32 v98, v46, v83
	s_movk_i32 s10, 0xffd4
	v_lshlrev_b32_e32 v46, 4, v98
	v_mov_b32_e32 v47, v1
	v_mul_lo_u32 v194, v186, s10
	s_movk_i32 s10, 0x580
	v_mul_u32_u24_e32 v192, 0x84, v53
	s_mov_b32 s18, 44
	v_add_u32_e32 v193, 44, v52
	v_mov_b32_e32 v99, v1
	v_lshl_add_u64 v[100:101], v[48:49], 1, v[50:51]
	v_lshl_add_u64 v[102:103], s[90:91], 0, v[46:47]
	v_mul_lo_u32 v195, v186, s10
	v_mov_b32_e32 v57, 0
	s_waitcnt vmcnt(0)
	v_mov_b32_e32 v91, v96
	v_mov_b64_e32 v[108:109], v[104:105]
	v_mov_b64_e32 v[110:111], v[106:107]
	v_readfirstlane_b32 s10, v65
	s_cmp_eq_u32 s10, 1
	s_cbranch_scc0 .Lwoff_ml_a
	s_barrier
	s_and_b64 vcc, exec, s[60:61]
	s_cbranch_vccnz .Lwoff_ml_a
	s_barrier

.LBB0_555:
	v_readfirstlane_b32 s10, v65
	s_cmp_eq_u32 s10, 0
	s_cbranch_scc0 .Lwoff_ml_b
	s_barrier
	s_and_b64 vcc, exec, s[60:61]
	s_cbranch_vccnz .Lwoff_ml_b
	s_barrier
